# attention phase: one static s_setprio 1 for waves 4-7 (younger half) at loop entry, reset at exit, on v53
# baseline (speedup 1.0000x reference)
.LBB0_1397:
	s_or_b64 exec, exec, s[8:9]
	v_and_b32_e32 v14, 63, v0
	v_or_b32_e32 v12, 0x200, v0
	v_mul_u32_u24_e32 v11, 0x410, v11
	v_lshlrev_b32_e32 v58, 4, v14
	v_add3_u32 v68, 0, v11, v58
	v_lshrrev_b32_e32 v11, 6, v12
	v_and_b32_e32 v12, 0x1f8, v10
	v_lshrrev_b32_e32 v20, 1, v0
	v_and_b32_e32 v15, 15, v0
	s_movk_i32 s7, 0x410
	v_mul_u32_u24_e32 v11, 0x410, v11
	v_lshlrev_b32_e32 v12, 1, v12
	v_and_b32_e32 v20, 16, v20
	v_lshrrev_b32_e32 v21, 2, v0
	v_add3_u32 v69, 0, v11, v12
	v_mad_u32_u24 v11, v15, s7, 0
	v_and_b32_e32 v17, 48, v0
	v_and_or_b32 v20, v21, 4, v20
	v_lshlrev_b32_e32 v21, 9, v15
	v_add_u32_e32 v18, v11, v17
	v_sub_u32_e32 v11, v11, v21
	v_lshl_add_u64 v[12:13], s[66:67], 0, v[58:59]
	s_mov_b64 s[8:9], 0x18300000
	v_lshl_add_u32 v71, v20, 1, v11
	v_bfe_u32 v11, v0, 2, 2
	v_lshl_add_u64 v[62:63], v[12:13], 0, s[8:9]
	v_or_b32_e32 v11, v20, v11
	s_add_i32 s8, 0, 0x16a00
	s_add_i32 s9, 0, 0x1ee00
	v_mul_u32_u24_e32 v20, 0x420, v11
	v_and_b32_e32 v21, 24, v10
	s_and_b64 s[0:1], s[0:1], exec
	v_add3_u32 v22, s8, v20, v21
	s_cselect_b32 s8, 32, s84
	s_lshl_b32 s0, s12, 2
	s_ashr_i32 s1, s12, 2
	s_add_i32 s16, s0, 0
	s_and_b32 s0, s12, 3
	s_lshl_b32 s13, s1, 9
	s_cmp_gt_u32 s0, 1
	v_lshl_or_b32 v23, s0, 4, v15
	s_movk_i32 s7, 0x420
	v_add_u32_e32 v26, 0xffffe0, v23
	v_mov_b32_e32 v27, s9
	s_cselect_b64 vcc, -1, 0
	s_lshl_b32 s0, s1, 14
	v_bfe_u32 v16, v0, 4, 2
	v_mad_u32_u24 v11, v11, s7, 0
	v_mad_u32_u24 v24, v23, s7, 0
	v_mad_i32_i24 v26, v26, s7, v27
	s_add_i32 s7, s0, 0
	v_lshlrev_b32_e32 v12, 12, v16
	v_add_u32_e32 v25, 0xe600, v24
	s_cmp_lt_u32 s12, 4
	v_lshlrev_b32_e32 v23, 2, v23
	s_cselect_b64 s[0:1], -1, 0
	v_add3_u32 v76, s7, v12, v23
	v_cndmask_b32_e32 v12, v25, v26, vcc
	s_lshl_b32 s7, s12, 11
	v_mov_b32_e32 v27, 0xff800000
	s_lshl_b32 s18, s12, 1
	s_mul_i32 s20, s12, 0x420
	v_add_u32_e32 v75, 0, v23
	v_add_u32_e32 v23, s13, v12
	s_add_i32 s7, s7, 0
	v_lshlrev_b32_e32 v12, 2, v14
	v_add3_u32 v20, s9, v20, v21
	v_cndmask_b32_e64 v72, 0, v27, s[0:1]
	s_lshl_b32 s0, s12, 6
	s_add_i32 s21, s20, 0
	s_add_i32 s9, s9, s20
	v_add_u32_e32 v78, s7, v12
	s_or_b32 s7, s18, 1
	s_ashr_i32 s1, s0, 31
	s_add_i32 s22, s21, 0xe600
	v_add_u32_e32 v77, s9, v58
	s_lshl_b32 s9, s7, 10
	v_lshl_add_u32 v19, v14, 1, 0
	v_mul_u32_u24_e32 v13, 14, v14
	s_lshl_b32 s19, s12, 7
	v_add_u32_e32 v73, s21, v58
	v_add_u32_e32 v74, s22, v58
	s_add_i32 s9, s9, 0
	v_lshlrev_b32_e32 v58, 10, v15
	s_lshl_b64 s[0:1], s[0:1], 1
	v_add_u32_e32 v79, s9, v12
	v_add3_u32 v80, v11, v21, s19
	v_add3_u32 v11, v19, v13, s20
	v_lshl_add_u64 v[12:13], s[10:11], 0, v[58:59]
	v_lshlrev_b32_e32 v58, 3, v16
	s_add_u32 s0, s66, s0
	v_lshl_add_u64 v[12:13], v[12:13], 0, v[58:59]
	s_addc_u32 s1, s67, s1
	v_add_u32_e32 v24, s13, v24
	s_mulk_i32 s7, 0x210
	v_add_u32_e32 v82, 0xe600, v11
	v_lshl_add_u64 v[12:13], s[0:1], 0, v[12:13]
	s_mov_b64 s[0:1], 0x3cca0040
	s_ashr_i32 s9, s8, 31
	v_mov_b32_e32 v11, s16
	v_lshl_add_u32 v70, v0, 2, 0
	s_mov_b32 s17, 0xff800000
	v_add_u32_e32 v81, 0xe600, v80
	v_lshl_add_u64 v[64:65], v[12:13], 0, s[0:1]
	s_lshl_b64 s[0:1], s[8:9], 14
	v_add_u32_e32 v83, s13, v18
	v_add_u32_e32 v84, v24, v17
	v_add_u32_e32 v85, v23, v17
	s_movk_i32 s9, 0x7fff
	v_add_u32_e32 v86, s20, v19
	v_add_u32_e32 v87, s7, v19
	v_lshlrev_b32_e32 v66, 1, v10
	v_add_u32_e32 v88, s19, v22
	v_add_u32_e32 v89, s19, v20
	v_add_u32_e32 v90, 0xe000, v11
	v_add_u32_e32 v91, 0xe400, v11
	v_readfirstlane_b32 s94, v0
	s_nop 3
	s_and_b32 s94, s94, 0x3ff
	s_lshr_b32 s94, s94, 6
	s_cmp_ge_u32 s94, 4
	s_cbranch_scc0 .Lat_prio_done
	s_setprio 1
.Lat_prio_done:
	s_branch .LBB0_1400
.LBB0_1398:
	s_or_b64 exec, exec, s[12:13]

.LBB0_1405:
	s_setprio 0
	s_cmp_lt_u32 s93, 11
	s_cbranch_scc1 .LBB0_1459
	s_waitcnt vmcnt(0)
	s_barrier
	s_mov_b64 s[0:1], exec
	v_readlane_b32 s4, v254, 37
	v_readlane_b32 s5, v254, 38
	s_and_b64 s[4:5], s[0:1], s[4:5]
	s_mov_b64 exec, s[4:5]
	s_cbranch_execz .LBB0_1458
	s_add_u32 s4, s66, 0x200
	s_addc_u32 s5, s67, 0
	s_add_i32 s3, 0, 0x27f20
	v_mov_b32_e32 v1, s3
	s_waitcnt vmcnt(0) expcnt(0) lgkmcnt(0)
	ds_read_b32 v3, v1
	s_add_i32 s3, 0, 0x27f24
	v_mov_b32_e32 v1, s3
	ds_read_b32 v1, v1
	s_waitcnt lgkmcnt(1)
	v_cmp_ne_u32_e32 vcc, 0, v3
	s_cbranch_vccnz .LBB0_1422
	v_readlane_b32 s10, v254, 2
	s_add_u32 s6, s66, 0x1000
	v_readlane_b32 s11, v254, 3
	s_addc_u32 s7, s67, 0
	s_load_dwordx2 s[14:15], s[10:11], 0x4
	s_add_u32 s8, s66, 0x1100
	s_addc_u32 s9, s67, 0
	s_add_u32 s10, s66, 0x1200
	s_addc_u32 s11, s67, 0
	s_add_u32 s12, s66, 0x1300
	s_waitcnt lgkmcnt(0)
	s_mul_i32 s3, s14, s84
	s_addc_u32 s13, s67, 0
	s_mul_i32 s3, s3, s15
	s_mov_b32 s20, 1
	v_mov_b32_e32 v17, 0
	s_branch .LBB0_1410
